# MLA attention loop: stagger + K/V tile global prefetch two steps ahead (two register sets, v188-199)
# baseline (speedup 1.0000x reference)
; #define LAS __attribute__((address_space(3)))
; __device__ __forceinline__ bf16_t bf1(float x) { return (bf16_t)(cvtpk(x, x) & 0xffffu); }
; __device__ __forceinline__ void mla_block(int bh, int sb, int tid, int lane, int wave, LAS unsigned char* lds, const bf16_t* __restrict__ QM, const bf16_t* __restrict__ KVM, const bf16_t* __restrict__ KPE, ...
;     ...
;     v4u rk, rr, rv;
;     rk = *(const v4u*)gKn; rr = *(const v4u*)gKr; rv = *(const v4u*)gVt;
; #pragma unroll
;     for (int j = 0; j < 8; ++j) { const float cs = j < 4 ? rc0_[j & 3] : rc1_[j & 3], sn = j < 4 ? rs0_[j & 3] : rs1_[j & 3];
;         const float x1 = bf2f((bf16_t)qf[4][j]), x2 = bf2f((bf16_t)qf[5][j]);
;         qf[4][j] = (short)bf1(x1 * cs - x2 * sn); qf[5][j] = (short)bf1(x2 * cs + x1 * sn); }
;     *(LAS v4u*)(lds + lKn) = rk; if (tid < 256) *(LAS v4u*)(lds + lKr) = rr; *(LAS u32x2*)(lds + lVt) = (u32x2){rv.x, rv.y}; *(LAS u32x2*)(lds + lVt + 8) = (u32x2){rv.z, rv.w};
;     __syncthreads();
; #pragma unroll 1
;     for (int step = 0; step < nsteps; ++step) {
;         const int nx = (step + 1 < nsteps) ? step + 1 : step;
;         rk = *(const v4u*)(gKn + (size_t)nx * 64 * 512); rr = *(const v4u*)(gKr + (size_t)nx * 64 * 32); rv = *(const v4u*)(gVt + nx * 64);
.LBB0_1592:
	s_or_b64 exec, exec, s[38:39]
	v_and_b32_e32 v35, 0xffff0000, v16
	v_lshlrev_b32_e32 v34, 16, v16
	v_and_b32_e32 v33, 0xffff0000, v20
	v_lshlrev_b32_e32 v32, 16, v20
	v_pk_mul_f32 v[36:37], v[24:25], v[34:35]
	v_lshlrev_b32_e32 v20, 16, v17
	v_pk_fma_f32 v[36:37], v[28:29], v[32:33], v[36:37]
	v_pk_mul_f32 v[28:29], v[28:29], v[34:35]
	s_waitcnt vmcnt(0)
	ds_write2_b64 v1, v[4:5], v[6:7] offset1:1
	v_pk_fma_f32 v[24:25], v[24:25], v[32:33], v[28:29] neg_lo:[0,0,1] neg_hi:[0,0,1]
	v_mov_b32_e32 v3, v2
	v_cvt_pk_bf16_f32 v88, v24, v25
	v_and_b32_e32 v25, 0xffff0000, v21
	v_lshlrev_b32_e32 v24, 16, v21
	v_and_b32_e32 v21, 0xffff0000, v17
	v_pk_mul_f32 v[16:17], v[26:27], v[20:21]
	v_mov_b32_e32 v4, v2
	v_pk_fma_f32 v[16:17], v[30:31], v[24:25], v[16:17]
	v_mov_b32_e32 v5, v2
	v_cvt_pk_bf16_f32 v85, v16, v17
	v_pk_mul_f32 v[16:17], v[30:31], v[20:21]
	v_and_b32_e32 v21, 0xffff0000, v18
	v_pk_fma_f32 v[16:17], v[26:27], v[24:25], v[16:17] neg_lo:[0,0,1] neg_hi:[0,0,1]
	v_lshlrev_b32_e32 v20, 16, v18
	v_cvt_pk_bf16_f32 v89, v16, v17
	v_and_b32_e32 v17, 0xffff0000, v22
	v_lshlrev_b32_e32 v16, 16, v22
	v_pk_mul_f32 v[24:25], v[12:13], v[16:17]
	v_pk_mul_f32 v[12:13], v[12:13], v[20:21]
	v_pk_fma_f32 v[24:25], v[8:9], v[20:21], v[24:25]
	v_pk_fma_f32 v[8:9], v[8:9], v[16:17], v[12:13] neg_lo:[0,0,1] neg_hi:[0,0,1]
	v_and_b32_e32 v13, 0xffff0000, v19
	v_cvt_pk_bf16_f32 v90, v8, v9
	v_and_b32_e32 v9, 0xffff0000, v23
	v_lshlrev_b32_e32 v8, 16, v23
	v_lshlrev_b32_e32 v12, 16, v19
	v_pk_mul_f32 v[16:17], v[14:15], v[8:9]
	v_cvt_pk_bf16_f32 v86, v24, v25
	v_pk_fma_f32 v[16:17], v[10:11], v[12:13], v[16:17]
	v_pk_mul_f32 v[12:13], v[14:15], v[12:13]
	v_cvt_pk_bf16_f32 v87, v16, v17
	v_pk_fma_f32 v[8:9], v[10:11], v[8:9], v[12:13] neg_lo:[0,0,1] neg_hi:[0,0,1]
	v_mov_b32_e32 v16, v2
	v_mov_b32_e32 v17, v2
	v_cvt_pk_bf16_f32 v91, v8, v9
	v_mov_b32_e32 v6, v2
	v_mov_b32_e32 v7, v2
	v_mov_b32_e32 v8, v2
	v_mov_b32_e32 v9, v2
	v_mov_b32_e32 v10, v2
	v_mov_b32_e32 v11, v2
	v_mov_b32_e32 v12, v2
	v_mov_b32_e32 v13, v2
	v_mov_b32_e32 v14, v2
	v_mov_b32_e32 v15, v2
	v_mov_b64_e32 v[34:35], v[16:17]
	s_lshl_b32 s19, s0, 2
	v_mov_b64_e32 v[32:33], v[14:15]
	v_mov_b64_e32 v[30:31], v[12:13]
	v_mov_b64_e32 v[28:29], v[10:11]
	v_mov_b64_e32 v[26:27], v[8:9]
	v_mov_b64_e32 v[24:25], v[6:7]
	v_mov_b64_e32 v[22:23], v[4:5]
	v_mov_b64_e32 v[20:21], v[2:3]
	v_mov_b64_e32 v[18:19], v[16:17]
	v_or_b32_e32 v159, s18, v136
	v_cvt_pk_bf16_f32 v84, v36, v37
	s_add_i32 s19, s19, 4
	s_addk_i32 s21, 0x100
	s_mov_b32 s40, 0
	v_mov_b32_e32 v163, 0xf149f2ca
	v_mov_b32_e32 v161, 0
	v_mov_b64_e32 v[16:17], v[14:15]
	v_mov_b64_e32 v[14:15], v[12:13]
	v_mov_b64_e32 v[12:13], v[10:11]
	v_mov_b64_e32 v[10:11], v[8:9]
	v_mov_b64_e32 v[8:9], v[6:7]
	v_mov_b64_e32 v[6:7], v[4:5]
	v_mov_b64_e32 v[4:5], v[2:3]
	s_mov_b32 s0, 0
	s_mov_b32 s12, 1
	s_lshl_b64 s[2:3], s[12:13], 16
	v_lshl_add_u64 v[36:37], v[168:169], 0, s[2:3]
	s_lshl_b64 s[2:3], s[12:13], 12
	s_lshl_b32 s12, s12, 6
	v_lshl_add_u64 v[38:39], v[170:171], 0, s[2:3]
	global_load_dwordx4 v[188:191], v[36:37], off
	global_load_dwordx4 v[192:195], v[38:39], off
	v_lshl_add_u64 v[36:37], s[12:13], 1, v[172:173]
	global_load_dwordx4 v[196:199], v[36:37], off
	s_mov_b32 s12, 2
	s_lshl_b64 s[2:3], s[12:13], 16
	v_lshl_add_u64 v[36:37], v[168:169], 0, s[2:3]
	s_lshl_b64 s[2:3], s[12:13], 12
	s_lshl_b32 s12, s12, 6
	v_lshl_add_u64 v[38:39], v[170:171], 0, s[2:3]
	global_load_dwordx4 v[100:103], v[36:37], off
	global_load_dwordx4 v[92:95], v[38:39], off
	v_lshl_add_u64 v[36:37], s[12:13], 1, v[172:173]
	global_load_dwordx4 v[96:99], v[36:37], off
	s_waitcnt lgkmcnt(0)
	s_barrier
	s_cmp_eq_u64 s[8:9], 0
	s_cbranch_scc0 .Lmla_lead_in
	s_barrier

; #define LAS __attribute__((address_space(3)))
; __device__ __forceinline__ int crow(int r, int hi) { return (r & 3) + 8 * (r >> 2) + 4 * hi; }
; __device__ __forceinline__ void mla_block(int bh, int sb, int tid, int lane, int wave, LAS unsigned char* lds, const bf16_t* __restrict__ QM, const bf16_t* __restrict__ KVM, const bf16_t* __restrict__ KPE, ...
;     ...
;             float tmax = -1e30f;
; #pragma unroll
;             for (int sub = 0; sub < 2; ++sub) { const int s0 = 64 * step + 32 * sub;
;                 if (s0 + 31 > q0) {
; #pragma unroll
;                     for (int r = 0; r < 16; ++r) if ((s0 + crow(r, hi)) > t) acc[sub][r] = -1e30f; }
; #pragma unroll
;                 for (int r = 0; r < 16; ++r) tmax = fmaxf(tmax, acc[sub][r]); }
;     ...
;         LAS unsigned char* nb = lds + ((step + 1) & 1) * ML_STAGE;
;         *(LAS v4u*)(nb + lKn) = rk; if (tid < 256) *(LAS v4u*)(nb + lKr) = rr; *(LAS u32x2*)(nb + lVt) = (u32x2){rv.x, rv.y}; *(LAS u32x2*)(nb + lVt + 8) = (u32x2){rv.z, rv.w};
;         __syncthreads();
.Lmla_stage:
	s_add_i32 s12, s41, 2
	s_add_i32 s2, s19, -1
	s_min_u32 s12, s12, s2
	s_bitcmp1_b32 s41, 0
	s_cselect_b32 s0, 0x5600, 0
	s_add_i32 s0, s0, 0
	s_bitcmp1_b32 s41, 0
	s_cbranch_scc1 .Lmla_stage_odd
	v_add_u32_e32 v3, s0, v150
	s_waitcnt vmcnt(5)
	ds_write_b128 v3, v[100:103]
	s_and_saveexec_b64 s[38:39], s[8:9]
	s_cbranch_execz .Lmla_st_e
	v_add_u32_e32 v3, s0, v181
	s_waitcnt vmcnt(4)
	ds_write_b128 v3, v[92:95] offset:128
.Lmla_st_e:
	s_or_b64 exec, exec, s[38:39]
	v_add_u32_e32 v3, s0, v152
	v_add_u32_e32 v3, 0x3400, v3
	s_waitcnt vmcnt(3)
	ds_write2_b64 v3, v[96:97], v[98:99] offset1:1
	s_lshl_b64 s[2:3], s[12:13], 16
	v_lshl_add_u64 v[184:185], v[168:169], 0, s[2:3]
	s_lshl_b64 s[2:3], s[12:13], 12
	s_lshl_b32 s12, s12, 6
	v_lshl_add_u64 v[186:187], v[170:171], 0, s[2:3]
	global_load_dwordx4 v[100:103], v[184:185], off
	global_load_dwordx4 v[92:95], v[186:187], off
	v_lshl_add_u64 v[184:185], s[12:13], 1, v[172:173]
	global_load_dwordx4 v[96:99], v[184:185], off
	s_branch .Lmla_stage_done
.Lmla_stage_odd:
	v_add_u32_e32 v3, s0, v150
	s_waitcnt vmcnt(5)
	ds_write_b128 v3, v[188:191]
	s_and_saveexec_b64 s[38:39], s[8:9]
	s_cbranch_execz .Lmla_st_o
	v_add_u32_e32 v3, s0, v181
	s_waitcnt vmcnt(4)
	ds_write_b128 v3, v[192:195] offset:128
.Lmla_st_o:
	s_or_b64 exec, exec, s[38:39]
	v_add_u32_e32 v3, s0, v152
	v_add_u32_e32 v3, 0x3400, v3
	s_waitcnt vmcnt(3)
	ds_write2_b64 v3, v[196:197], v[198:199] offset1:1
	s_lshl_b64 s[2:3], s[12:13], 16
	v_lshl_add_u64 v[184:185], v[168:169], 0, s[2:3]
	s_lshl_b64 s[2:3], s[12:13], 12
	s_lshl_b32 s12, s12, 6
	v_lshl_add_u64 v[186:187], v[170:171], 0, s[2:3]
	global_load_dwordx4 v[188:191], v[184:185], off
	global_load_dwordx4 v[192:195], v[186:187], off
	v_lshl_add_u64 v[184:185], s[12:13], 1, v[172:173]
	global_load_dwordx4 v[196:199], v[184:185], off
.Lmla_stage_done:
	s_waitcnt lgkmcnt(0)
	s_barrier
	s_cmp_gt_i32 s40, s18
	s_cbranch_scc1 .LBB0_1601
	s_add_i32 s0, s40, 31
	s_cmp_le_i32 s0, s18
	v_add_u32_e32 v3, s40, v147
	s_cbranch_scc1 .LBB0_1596
	v_cmp_gt_i32_e32 vcc, v3, v159
	s_nop 6
	v_cndmask_b32_e32 v165, v52, v183, vcc
	v_cmp_lt_i32_e32 vcc, v3, v159
	s_nop 1
	v_cndmask_b32_e32 v52, v165, v52, vcc
	v_add_u32_e32 v165, 2, v3
	v_cndmask_b32_e32 v53, v183, v53, vcc
	v_cmp_le_i32_e32 vcc, v165, v159
	v_add_u32_e32 v165, 3, v3
	s_nop 0
	v_cndmask_b32_e32 v54, v183, v54, vcc
	v_cmp_le_i32_e32 vcc, v165, v159
	v_add_u32_e32 v165, 8, v3
	s_nop 0
	v_cndmask_b32_e32 v55, v183, v55, vcc
	v_cmp_le_i32_e32 vcc, v165, v159
	v_add_u32_e32 v165, 9, v3
	s_nop 0
	v_cndmask_b32_e32 v56, v183, v56, vcc
	v_cmp_le_i32_e32 vcc, v165, v159
	v_add_u32_e32 v165, 10, v3
	s_nop 0
	v_cndmask_b32_e32 v57, v183, v57, vcc
	v_cmp_le_i32_e32 vcc, v165, v159
	v_add_u32_e32 v165, 11, v3
	s_nop 0
	v_cndmask_b32_e32 v58, v183, v58, vcc
	v_cmp_le_i32_e32 vcc, v165, v159
	v_add_u32_e32 v165, 16, v3
	s_nop 0
	v_cndmask_b32_e32 v59, v183, v59, vcc
	v_cmp_le_i32_e32 vcc, v165, v159
	v_add_u32_e32 v165, 17, v3
	s_nop 0
	v_cndmask_b32_e32 v60, v183, v60, vcc
	v_cmp_le_i32_e32 vcc, v165, v159
	v_add_u32_e32 v165, 18, v3
	s_nop 0
	v_cndmask_b32_e32 v61, v183, v61, vcc
	v_cmp_le_i32_e32 vcc, v165, v159
	v_add_u32_e32 v165, 19, v3
	s_nop 0
	v_cndmask_b32_e32 v62, v183, v62, vcc
	v_cmp_le_i32_e32 vcc, v165, v159
	v_add_u32_e32 v165, 24, v3
	s_nop 0
	v_cndmask_b32_e32 v63, v183, v63, vcc
	v_cmp_le_i32_e32 vcc, v165, v159
	v_add_u32_e32 v165, 25, v3
	s_nop 0
	v_cndmask_b32_e32 v64, v183, v64, vcc
	v_cmp_le_i32_e32 vcc, v165, v159
	v_add_u32_e32 v165, 26, v3
	s_nop 0
	v_cndmask_b32_e32 v65, v183, v65, vcc
	v_cmp_le_i32_e32 vcc, v165, v159
	v_add_u32_e32 v165, 27, v3
	s_nop 0
	v_cndmask_b32_e32 v66, v183, v66, vcc
	v_cmp_le_i32_e32 vcc, v165, v159
	s_nop 1
	v_cndmask_b32_e32 v67, v183, v67, vcc
